# v49 + phase B row loop: loop-invariant gate-bias load hoisted out; removed per-row vmcnt(0) that drained next-row prefetch and H stores
# speedup vs baseline: 1.0047x; 1.0029x over previous
.LBB0_114:
	s_or_b64 exec, exec, s[26:27]
	s_and_saveexec_b64 s[98:99], s[6:7]
	global_load_dword v170, v[72:73], off
	s_mov_b64 exec, s[98:99]
	v_lshl_add_u32 v106, s2, 6, v86
	v_ashrrev_i32_e32 v107, 31, v106
	v_lshlrev_b64 v[106:107], 13, v[106:107]
	v_lshl_add_u64 v[106:107], v[70:71], 0, v[106:107]
	global_load_dwordx4 v[60:63], v[106:107], off nt
	global_load_dwordx4 v[56:59], v[106:107], off offset:1024 nt
	global_load_dwordx4 v[52:55], v[106:107], off offset:2048 nt
	global_load_dwordx4 v[48:51], v[106:107], off offset:3072 nt
	v_add_co_u32_e32 v106, vcc, 0x1000, v106
	s_nop 1
	v_addc_co_u32_e32 v107, vcc, 0, v107, vcc
	global_load_dwordx4 v[44:47], v[106:107], off nt
	global_load_dwordx4 v[40:43], v[106:107], off offset:1024 nt
	global_load_dwordx4 v[36:39], v[106:107], off offset:2048 nt
	global_load_dwordx4 v[32:35], v[106:107], off offset:3072 nt
	s_and_saveexec_b64 s[26:27], s[4:5]
	s_cbranch_execz .LBB0_117
	s_mov_b32 s3, 0xd020
	v_add_u32_e32 v101, 0x0, v64
	v_ashrrev_i32_e32 v150, 1, v101
	v_lshlrev_b32_e32 v102, 2, v101
	v_and_b32_e32 v102, 4, v102
	v_mov_b64_e32 v[104:105], s[70:71]
	v_mad_i64_i32 v[104:105], s[36:37], v150, s3, v[104:105]
	v_lshlrev_b32_e32 v66, 2, v102
	v_lshl_add_u64 v[104:105], v[104:105], 0, v[66:67]
	v_add_co_u32_e32 v104, vcc, 0x9000, v104
	v_lshlrev_b32_e32 v150, 2, v150
	v_lshlrev_b32_e32 v102, 13, v102
	v_addc_co_u32_e32 v105, vcc, 0, v105, vcc
	global_load_dwordx4 v[110:113], v[104:105], off
	v_add3_u32 v150, 0, v150, v102
	v_add_u32_e32 v101, 0x200, v64
	v_ashrrev_i32_e32 v151, 1, v101
	v_lshlrev_b32_e32 v102, 2, v101
	v_and_b32_e32 v102, 4, v102
	v_mov_b64_e32 v[104:105], s[70:71]
	v_mad_i64_i32 v[104:105], s[36:37], v151, s3, v[104:105]
	v_lshlrev_b32_e32 v66, 2, v102
	v_lshl_add_u64 v[104:105], v[104:105], 0, v[66:67]
	v_add_co_u32_e32 v104, vcc, 0x9000, v104
	v_lshlrev_b32_e32 v151, 2, v151
	v_lshlrev_b32_e32 v102, 13, v102
	v_addc_co_u32_e32 v105, vcc, 0, v105, vcc
	global_load_dwordx4 v[114:117], v[104:105], off
	v_add3_u32 v151, 0, v151, v102
	v_add_u32_e32 v101, 0x400, v64
	v_ashrrev_i32_e32 v152, 1, v101
	v_lshlrev_b32_e32 v102, 2, v101
	v_and_b32_e32 v102, 4, v102
	v_mov_b64_e32 v[104:105], s[70:71]
	v_mad_i64_i32 v[104:105], s[36:37], v152, s3, v[104:105]
	v_lshlrev_b32_e32 v66, 2, v102
	v_lshl_add_u64 v[104:105], v[104:105], 0, v[66:67]
	v_add_co_u32_e32 v104, vcc, 0x9000, v104
	v_lshlrev_b32_e32 v152, 2, v152
	v_lshlrev_b32_e32 v102, 13, v102
	v_addc_co_u32_e32 v105, vcc, 0, v105, vcc
	global_load_dwordx4 v[118:121], v[104:105], off
	v_add3_u32 v152, 0, v152, v102
	v_add_u32_e32 v101, 0x600, v64
	v_ashrrev_i32_e32 v153, 1, v101
	v_lshlrev_b32_e32 v102, 2, v101
	v_and_b32_e32 v102, 4, v102
	v_mov_b64_e32 v[104:105], s[70:71]
	v_mad_i64_i32 v[104:105], s[36:37], v153, s3, v[104:105]
	v_lshlrev_b32_e32 v66, 2, v102
	v_lshl_add_u64 v[104:105], v[104:105], 0, v[66:67]
	v_add_co_u32_e32 v104, vcc, 0x9000, v104
	v_lshlrev_b32_e32 v153, 2, v153
	v_lshlrev_b32_e32 v102, 13, v102
	v_addc_co_u32_e32 v105, vcc, 0, v105, vcc
	global_load_dwordx4 v[122:125], v[104:105], off
	v_add3_u32 v153, 0, v153, v102
	v_add_u32_e32 v101, 0x800, v64
	v_ashrrev_i32_e32 v154, 1, v101
	v_lshlrev_b32_e32 v102, 2, v101
	v_and_b32_e32 v102, 4, v102
	v_mov_b64_e32 v[104:105], s[70:71]
	v_mad_i64_i32 v[104:105], s[36:37], v154, s3, v[104:105]
	v_lshlrev_b32_e32 v66, 2, v102
	v_lshl_add_u64 v[104:105], v[104:105], 0, v[66:67]
	v_add_co_u32_e32 v104, vcc, 0x9000, v104
	v_lshlrev_b32_e32 v154, 2, v154
	v_lshlrev_b32_e32 v102, 13, v102
	v_addc_co_u32_e32 v105, vcc, 0, v105, vcc
	global_load_dwordx4 v[126:129], v[104:105], off
	v_add3_u32 v154, 0, v154, v102
	v_add_u32_e32 v101, 0xa00, v64
	v_ashrrev_i32_e32 v155, 1, v101
	v_lshlrev_b32_e32 v102, 2, v101
	v_and_b32_e32 v102, 4, v102
	v_mov_b64_e32 v[104:105], s[70:71]
	v_mad_i64_i32 v[104:105], s[36:37], v155, s3, v[104:105]
	v_lshlrev_b32_e32 v66, 2, v102
	v_lshl_add_u64 v[104:105], v[104:105], 0, v[66:67]
	v_add_co_u32_e32 v104, vcc, 0x9000, v104
	v_lshlrev_b32_e32 v155, 2, v155
	v_lshlrev_b32_e32 v102, 13, v102
	v_addc_co_u32_e32 v105, vcc, 0, v105, vcc
	global_load_dwordx4 v[130:133], v[104:105], off
	v_add3_u32 v155, 0, v155, v102
	v_add_u32_e32 v101, 0xc00, v64
	v_ashrrev_i32_e32 v156, 1, v101
	v_lshlrev_b32_e32 v102, 2, v101
	v_and_b32_e32 v102, 4, v102
	v_mov_b64_e32 v[104:105], s[70:71]
	v_mad_i64_i32 v[104:105], s[36:37], v156, s3, v[104:105]
	v_lshlrev_b32_e32 v66, 2, v102
	v_lshl_add_u64 v[104:105], v[104:105], 0, v[66:67]
	v_add_co_u32_e32 v104, vcc, 0x9000, v104
	v_lshlrev_b32_e32 v156, 2, v156
	v_lshlrev_b32_e32 v102, 13, v102
	v_addc_co_u32_e32 v105, vcc, 0, v105, vcc
	global_load_dwordx4 v[134:137], v[104:105], off
	v_add3_u32 v156, 0, v156, v102
	v_add_u32_e32 v101, 0xe00, v64
	v_ashrrev_i32_e32 v157, 1, v101
	v_lshlrev_b32_e32 v102, 2, v101
	v_and_b32_e32 v102, 4, v102
	v_mov_b64_e32 v[104:105], s[70:71]
	v_mad_i64_i32 v[104:105], s[36:37], v157, s3, v[104:105]
	v_lshlrev_b32_e32 v66, 2, v102
	v_lshl_add_u64 v[104:105], v[104:105], 0, v[66:67]
	v_add_co_u32_e32 v104, vcc, 0x9000, v104
	v_lshlrev_b32_e32 v157, 2, v157
	v_lshlrev_b32_e32 v102, 13, v102
	v_addc_co_u32_e32 v105, vcc, 0, v105, vcc
	global_load_dwordx4 v[138:141], v[104:105], off
	v_add3_u32 v157, 0, v157, v102
	s_waitcnt vmcnt(7)
	ds_write2st64_b32 v150, v110, v111 offset0:64 offset1:96
	ds_write2st64_b32 v150, v112, v113 offset0:128 offset1:160
	s_waitcnt vmcnt(6)
	ds_write2st64_b32 v151, v114, v115 offset0:64 offset1:96
	ds_write2st64_b32 v151, v116, v117 offset0:128 offset1:160
	s_waitcnt vmcnt(5)
	ds_write2st64_b32 v152, v118, v119 offset0:64 offset1:96
	ds_write2st64_b32 v152, v120, v121 offset0:128 offset1:160
	s_waitcnt vmcnt(4)
	ds_write2st64_b32 v153, v122, v123 offset0:64 offset1:96
	ds_write2st64_b32 v153, v124, v125 offset0:128 offset1:160
	s_waitcnt vmcnt(3)
	ds_write2st64_b32 v154, v126, v127 offset0:64 offset1:96
	ds_write2st64_b32 v154, v128, v129 offset0:128 offset1:160
	s_waitcnt vmcnt(2)
	ds_write2st64_b32 v155, v130, v131 offset0:64 offset1:96
	ds_write2st64_b32 v155, v132, v133 offset0:128 offset1:160
	s_waitcnt vmcnt(1)
	ds_write2st64_b32 v156, v134, v135 offset0:64 offset1:96
	ds_write2st64_b32 v156, v136, v137 offset0:128 offset1:160
	s_waitcnt vmcnt(0)
	ds_write2st64_b32 v157, v138, v139 offset0:64 offset1:96
	ds_write2st64_b32 v157, v140, v141 offset0:128 offset1:160
	s_nop 0
	s_nop 0
	s_nop 0
	s_nop 0
	s_nop 0
	s_nop 0
	s_nop 0
	s_nop 0
	s_nop 0
	s_nop 0
	s_nop 0
	s_nop 0
	s_nop 0

.LBB0_121:
	v_mul_f32_e32 v66, v61, v61
	v_mul_f32_e32 v75, v57, v57
	v_fmac_f32_e32 v66, v60, v60
	v_fmac_f32_e32 v75, v56, v56
	v_fmac_f32_e32 v66, v62, v62
	v_fmac_f32_e32 v75, v58, v58
	v_fmac_f32_e32 v66, v63, v63
	v_fmac_f32_e32 v75, v59, v59
	v_add_f32_e32 v66, v66, v75
	v_mul_f32_e32 v75, v53, v53
	v_fmac_f32_e32 v75, v52, v52
	v_fmac_f32_e32 v75, v54, v54
	v_fmac_f32_e32 v75, v55, v55
	v_add_f32_e32 v66, v66, v75
	v_mul_f32_e32 v75, v49, v49
	v_fmac_f32_e32 v75, v48, v48
	v_fmac_f32_e32 v75, v50, v50
	v_fmac_f32_e32 v75, v51, v51
	v_add_f32_e32 v66, v66, v75
	v_mul_f32_e32 v75, v45, v45
	v_fmac_f32_e32 v75, v44, v44
	v_fmac_f32_e32 v75, v46, v46
	v_fmac_f32_e32 v75, v47, v47
	v_add_f32_e32 v66, v66, v75
	v_mul_f32_e32 v75, v41, v41
	v_fmac_f32_e32 v75, v40, v40
	v_fmac_f32_e32 v75, v42, v42
	v_fmac_f32_e32 v75, v43, v43
	v_add_f32_e32 v66, v66, v75
	v_mul_f32_e32 v75, v37, v37
	v_fmac_f32_e32 v75, v36, v36
	v_fmac_f32_e32 v75, v38, v38
	v_fmac_f32_e32 v75, v39, v39
	v_add_f32_e32 v66, v66, v75
	v_mul_f32_e32 v75, v33, v33
	v_fmac_f32_e32 v75, v32, v32
	v_fmac_f32_e32 v75, v34, v34
	v_fmac_f32_e32 v75, v35, v35
	v_add_f32_e32 v66, v66, v75
	ds_read_b128 v[102:105], v87
	ds_read_b128 v[106:109], v87 offset:8192
	v_add_f32_dpp v66, v66, v66 quad_perm:[1,0,3,2] row_mask:0xf bank_mask:0xf bound_ctrl:1
	ds_read_b128 v[110:113], v87 offset:16384
	v_ashrrev_i32_e32 v83, 31, v82
	v_add_f32_dpp v66, v66, v66 quad_perm:[2,3,0,1] row_mask:0xf bank_mask:0xf bound_ctrl:1
	v_lshlrev_b64 v[114:115], 12, v[82:83]
	s_nop 0
	v_add_f32_dpp v66, v66, v66 row_half_mirror row_mask:0xf bank_mask:0xf bound_ctrl:1
	s_nop 1
	v_add_f32_dpp v66, v66, v66 row_mirror row_mask:0xf bank_mask:0xf bound_ctrl:1
	s_nop 0
	v_readlane_b32 s34, v66, 16
	v_readlane_b32 s3, v66, 0
	s_nop 0
	v_mov_b32_e32 v75, s34
	v_add_f32_e32 v75, s3, v75
	v_readlane_b32 s3, v66, 32
	s_nop 1
	v_add_f32_e32 v75, s3, v75
	v_readlane_b32 s3, v66, 48
	s_nop 1
	v_add_f32_e32 v66, s3, v75
	v_fmamk_f32 v66, v66, 0x3a000000, v100
	s_mov_b32 s3, 0x800000
	v_mul_f32_e32 v75, 0x4b800000, v66
	v_cmp_gt_f32_e32 vcc, s3, v66
	s_nop 1
	v_cndmask_b32_e32 v66, v66, v75, vcc
	v_rsq_f32_e32 v66, v66
	s_nop 0
	v_mul_f32_e32 v75, 0x45800000, v66
	v_cndmask_b32_e32 v66, v66, v75, vcc
	v_pk_mul_f32 v[60:61], v[60:61], v[66:67] op_sel_hi:[1,0]
	v_pk_mul_f32 v[62:63], v[62:63], v[66:67] op_sel_hi:[1,0]
	s_waitcnt lgkmcnt(1)
	v_pk_fma_f32 v[106:107], v[102:103], v[60:61], v[106:107]
	v_pk_fma_f32 v[108:109], v[104:105], v[62:63], v[108:109]
	ds_read_b128 v[60:63], v87 offset:24576
	ds_read_b128 v[102:105], v87 offset:32768
	s_waitcnt lgkmcnt(2)
	v_mul_f32_e32 v75, v111, v107
	v_fmac_f32_e32 v75, v110, v106
	v_fmac_f32_e32 v75, v112, v108
	s_waitcnt lgkmcnt(1)
	v_mul_f32_e32 v61, v61, v107
	v_fmac_f32_e32 v61, v60, v106
	v_fmac_f32_e32 v61, v62, v108
	v_fmac_f32_e32 v61, v63, v109
	v_add_f32_e32 v81, 0, v61
	ds_read_b128 v[60:63], v87 offset:40960
	s_waitcnt lgkmcnt(1)
	v_mul_f32_e32 v101, v103, v107
	v_fmac_f32_e32 v101, v102, v106
	v_fmac_f32_e32 v101, v104, v108
	v_fmac_f32_e32 v101, v105, v109
	s_waitcnt lgkmcnt(0)
	v_mul_f32_e32 v61, v61, v107
	v_fmac_f32_e32 v61, v60, v106
	v_fmac_f32_e32 v61, v62, v108
	v_fmac_f32_e32 v61, v63, v109
	ds_read_b128 v[102:105], v87 offset:49152
	v_add_f32_e32 v116, 0, v61
	ds_read_b128 v[60:63], v87 offset:57344
	v_fmac_f32_e32 v75, v113, v109
	v_pk_mul_f32 v[56:57], v[56:57], v[66:67] op_sel_hi:[1,0]
	s_waitcnt lgkmcnt(1)
	v_mul_f32_e32 v103, v103, v107
	v_fmac_f32_e32 v103, v102, v106
	s_waitcnt lgkmcnt(0)
	v_mul_f32_e32 v61, v61, v107
	v_fmac_f32_e32 v61, v60, v106
	v_fmac_f32_e32 v103, v104, v108
	v_fmac_f32_e32 v61, v62, v108
	v_fmac_f32_e32 v103, v105, v109
	v_fmac_f32_e32 v61, v63, v109
	v_add_f32_e32 v117, 0, v103
	ds_read_b128 v[102:105], v88 offset:49152
	v_add_f32_e32 v118, 0, v61
	ds_read_b128 v[60:63], v88 offset:57344
	v_pk_mul_f32 v[58:59], v[58:59], v[66:67] op_sel_hi:[1,0]
	v_add_f32_e32 v75, 0, v75
	s_waitcnt lgkmcnt(1)
	v_mul_f32_e32 v103, v103, v107
	v_fmac_f32_e32 v103, v102, v106
	s_waitcnt lgkmcnt(0)
	v_mul_f32_e32 v110, v61, v107
	v_fmac_f32_e32 v110, v60, v106
	v_fmac_f32_e32 v110, v62, v108
	v_fmac_f32_e32 v110, v63, v109
	v_cvt_pk_bf16_f32 v62, v106, v107
	v_cvt_pk_bf16_f32 v63, v108, v109
	v_lshl_add_u64 v[60:61], v[76:77], 0, v[114:115]
	v_fmac_f32_e32 v103, v104, v108
	global_store_dwordx2 v[60:61], v[62:63], off
	v_fmac_f32_e32 v103, v105, v109
	v_add_f32_e32 v119, 0, v103
	ds_read_b128 v[102:105], v87 offset:1024
	ds_read_b128 v[106:109], v87 offset:9216
	v_add_f32_e32 v114, 0, v110
	ds_read_b128 v[110:113], v87 offset:17408
	v_add_f32_e32 v101, 0, v101
	v_pk_mul_f32 v[52:53], v[52:53], v[66:67] op_sel_hi:[1,0]
	s_waitcnt lgkmcnt(1)
	v_pk_fma_f32 v[62:63], v[58:59], v[104:105], v[108:109]
	v_pk_fma_f32 v[106:107], v[56:57], v[102:103], v[106:107]
	ds_read_b128 v[56:59], v87 offset:25600
	s_waitcnt lgkmcnt(1)
	v_mul_f32_e32 v102, v107, v111
	v_fmac_f32_e32 v102, v106, v110
	v_fmac_f32_e32 v102, v62, v112
	v_fmac_f32_e32 v102, v63, v113
	s_waitcnt lgkmcnt(0)
	v_mul_f32_e32 v57, v107, v57
	v_fmac_f32_e32 v57, v106, v56
	v_fmac_f32_e32 v57, v62, v58
	v_fmac_f32_e32 v57, v63, v59
	v_add_f32_e32 v75, v75, v102
	ds_read_b128 v[102:105], v87 offset:33792
	v_add_f32_e32 v81, v81, v57
	ds_read_b128 v[56:59], v87 offset:41984
	v_pk_mul_f32 v[54:55], v[54:55], v[66:67] op_sel_hi:[1,0]
	v_pk_mul_f32 v[48:49], v[48:49], v[66:67] op_sel_hi:[1,0]
	s_waitcnt lgkmcnt(1)
	v_mul_f32_e32 v103, v107, v103
	v_fmac_f32_e32 v103, v106, v102
	s_waitcnt lgkmcnt(0)
	v_mul_f32_e32 v57, v107, v57
	v_fmac_f32_e32 v57, v106, v56
	v_fmac_f32_e32 v103, v62, v104
	v_fmac_f32_e32 v57, v62, v58
	v_fmac_f32_e32 v103, v63, v105
	v_fmac_f32_e32 v57, v63, v59
	v_add_f32_e32 v101, v101, v103
	ds_read_b128 v[102:105], v87 offset:50176
	v_add_f32_e32 v110, v116, v57
	ds_read_b128 v[56:59], v87 offset:58368
	v_pk_mul_f32 v[50:51], v[50:51], v[66:67] op_sel_hi:[1,0]
	v_pk_mul_f32 v[44:45], v[44:45], v[66:67] op_sel_hi:[1,0]
	s_waitcnt lgkmcnt(1)
	v_mul_f32_e32 v103, v107, v103
	v_fmac_f32_e32 v103, v106, v102
	s_waitcnt lgkmcnt(0)
	v_mul_f32_e32 v57, v107, v57
	v_fmac_f32_e32 v57, v106, v56
	v_fmac_f32_e32 v103, v62, v104
	v_fmac_f32_e32 v57, v62, v58
	v_fmac_f32_e32 v103, v63, v105
	v_fmac_f32_e32 v57, v63, v59
	v_add_f32_e32 v111, v117, v103
	ds_read_b128 v[102:105], v89 offset:49152
	v_add_f32_e32 v112, v118, v57
	ds_read_b128 v[56:59], v89 offset:57344
	v_pk_mul_f32 v[46:47], v[46:47], v[66:67] op_sel_hi:[1,0]
	v_pk_mul_f32 v[40:41], v[40:41], v[66:67] op_sel_hi:[1,0]
	s_waitcnt lgkmcnt(1)
	v_mul_f32_e32 v103, v107, v103
	v_fmac_f32_e32 v103, v106, v102
	s_waitcnt lgkmcnt(0)
	v_mul_f32_e32 v108, v107, v57
	v_fmac_f32_e32 v108, v106, v56
	v_cvt_pk_bf16_f32 v56, v106, v107
	v_cvt_pk_bf16_f32 v57, v62, v63
	v_fmac_f32_e32 v103, v62, v104
	global_store_dwordx2 v[60:61], v[56:57], off offset:512
	v_fmac_f32_e32 v103, v63, v105
	v_fmac_f32_e32 v108, v62, v58
	v_add_f32_e32 v113, v119, v103
	v_fmac_f32_e32 v108, v63, v59
	ds_read_b128 v[56:59], v87 offset:2048
	ds_read_b128 v[102:105], v87 offset:10240
	v_add_f32_e32 v114, v114, v108
	ds_read_b128 v[106:109], v87 offset:18432
	v_pk_mul_f32 v[42:43], v[42:43], v[66:67] op_sel_hi:[1,0]
	v_pk_mul_f32 v[36:37], v[36:37], v[66:67] op_sel_hi:[1,0]
	s_waitcnt lgkmcnt(1)
	v_pk_fma_f32 v[62:63], v[54:55], v[58:59], v[104:105]
	v_pk_fma_f32 v[102:103], v[52:53], v[56:57], v[102:103]
	ds_read_b128 v[52:55], v87 offset:26624
	s_waitcnt lgkmcnt(1)
	v_mul_f32_e32 v56, v103, v107
	v_fmac_f32_e32 v56, v102, v106
	v_fmac_f32_e32 v56, v62, v108
	v_fmac_f32_e32 v56, v63, v109
	s_waitcnt lgkmcnt(0)
	v_mul_f32_e32 v53, v103, v53
	v_fmac_f32_e32 v53, v102, v52
	v_fmac_f32_e32 v53, v62, v54
	v_fmac_f32_e32 v53, v63, v55
	v_add_f32_e32 v75, v75, v56
	ds_read_b128 v[56:59], v87 offset:34816
	v_add_f32_e32 v81, v81, v53
	ds_read_b128 v[52:55], v87 offset:43008
	v_pk_mul_f32 v[38:39], v[38:39], v[66:67] op_sel_hi:[1,0]
	v_pk_mul_f32 v[32:33], v[32:33], v[66:67] op_sel_hi:[1,0]
	s_waitcnt lgkmcnt(1)
	v_mul_f32_e32 v57, v103, v57
	v_fmac_f32_e32 v57, v102, v56
	s_waitcnt lgkmcnt(0)
	v_mul_f32_e32 v53, v103, v53
	v_fmac_f32_e32 v53, v102, v52
	v_fmac_f32_e32 v57, v62, v58
	v_fmac_f32_e32 v53, v62, v54
	v_fmac_f32_e32 v57, v63, v59
	v_fmac_f32_e32 v53, v63, v55
	v_add_f32_e32 v101, v101, v57
	ds_read_b128 v[56:59], v87 offset:51200
	v_add_f32_e32 v106, v110, v53
	ds_read_b128 v[52:55], v87 offset:59392
	v_pk_mul_f32 v[34:35], v[34:35], v[66:67] op_sel_hi:[1,0]
	s_waitcnt lgkmcnt(1)
	v_mul_f32_e32 v57, v103, v57
	v_fmac_f32_e32 v57, v102, v56
	s_waitcnt lgkmcnt(0)
	v_mul_f32_e32 v53, v103, v53
	v_fmac_f32_e32 v53, v102, v52
	v_fmac_f32_e32 v57, v62, v58
	v_fmac_f32_e32 v53, v62, v54
	v_fmac_f32_e32 v57, v63, v59
	v_fmac_f32_e32 v53, v63, v55
	v_add_f32_e32 v107, v111, v57
	ds_read_b128 v[56:59], v90 offset:49152
	v_add_f32_e32 v108, v112, v53
	ds_read_b128 v[52:55], v90 offset:57344
	s_waitcnt lgkmcnt(1)
	v_mul_f32_e32 v57, v103, v57
	v_fmac_f32_e32 v57, v102, v56
	s_waitcnt lgkmcnt(0)
	v_mul_f32_e32 v104, v103, v53
	v_fmac_f32_e32 v104, v102, v52
	v_cvt_pk_bf16_f32 v52, v102, v103
	v_cvt_pk_bf16_f32 v53, v62, v63
	v_fmac_f32_e32 v57, v62, v58
	global_store_dwordx2 v[60:61], v[52:53], off offset:1024
	v_fmac_f32_e32 v57, v63, v59
	v_fmac_f32_e32 v104, v62, v54
	v_add_f32_e32 v109, v113, v57
	v_fmac_f32_e32 v104, v63, v55
	ds_read_b128 v[52:55], v87 offset:3072
	ds_read_b128 v[56:59], v87 offset:11264
	v_add_f32_e32 v62, v114, v104
	ds_read_b128 v[102:105], v87 offset:19456
	s_waitcnt lgkmcnt(1)
	v_pk_fma_f32 v[58:59], v[50:51], v[54:55], v[58:59]
	v_pk_fma_f32 v[56:57], v[48:49], v[52:53], v[56:57]
	ds_read_b128 v[48:51], v87 offset:27648
	s_waitcnt lgkmcnt(1)
	v_mul_f32_e32 v52, v57, v103
	v_fmac_f32_e32 v52, v56, v102
	v_fmac_f32_e32 v52, v58, v104
	v_fmac_f32_e32 v52, v59, v105
	s_waitcnt lgkmcnt(0)
	v_mul_f32_e32 v49, v57, v49
	v_fmac_f32_e32 v49, v56, v48
	v_fmac_f32_e32 v49, v58, v50
	v_fmac_f32_e32 v49, v59, v51
	v_add_f32_e32 v63, v75, v52
	ds_read_b128 v[52:55], v87 offset:35840
	v_add_f32_e32 v75, v81, v49
	ds_read_b128 v[48:51], v87 offset:44032
	s_waitcnt lgkmcnt(1)
	v_mul_f32_e32 v53, v57, v53
	v_fmac_f32_e32 v53, v56, v52
	s_waitcnt lgkmcnt(0)
	v_mul_f32_e32 v49, v57, v49
	v_fmac_f32_e32 v49, v56, v48
	v_fmac_f32_e32 v53, v58, v54
	v_fmac_f32_e32 v49, v58, v50
	v_fmac_f32_e32 v53, v59, v55
	v_fmac_f32_e32 v49, v59, v51
	v_add_f32_e32 v81, v101, v53
	ds_read_b128 v[52:55], v87 offset:52224
	v_add_f32_e32 v101, v106, v49
	ds_read_b128 v[48:51], v87 offset:60416
	s_waitcnt lgkmcnt(1)
	v_mul_f32_e32 v53, v57, v53
	v_fmac_f32_e32 v53, v56, v52
	s_waitcnt lgkmcnt(0)
	v_mul_f32_e32 v49, v57, v49
	v_fmac_f32_e32 v49, v56, v48
	v_fmac_f32_e32 v53, v58, v54
	v_fmac_f32_e32 v49, v58, v50
	v_fmac_f32_e32 v53, v59, v55
	v_fmac_f32_e32 v49, v59, v51
	v_add_f32_e32 v102, v107, v53
	ds_read_b128 v[52:55], v91 offset:49152
	v_add_f32_e32 v103, v108, v49
	ds_read_b128 v[48:51], v91 offset:57344
	s_waitcnt lgkmcnt(1)
	v_mul_f32_e32 v53, v57, v53
	v_fmac_f32_e32 v53, v56, v52
	s_waitcnt lgkmcnt(0)
	v_mul_f32_e32 v105, v57, v49
	v_fmac_f32_e32 v105, v56, v48
	v_cvt_pk_bf16_f32 v48, v56, v57
	v_cvt_pk_bf16_f32 v49, v58, v59
	v_fmac_f32_e32 v53, v58, v54
	global_store_dwordx2 v[60:61], v[48:49], off offset:1536
	v_fmac_f32_e32 v53, v59, v55
	v_fmac_f32_e32 v105, v58, v50
	v_add_f32_e32 v104, v109, v53
	v_fmac_f32_e32 v105, v59, v51
	ds_read_b128 v[48:51], v87 offset:4096
	ds_read_b128 v[52:55], v87 offset:12288
	ds_read_b128 v[56:59], v87 offset:20480
	v_add_f32_e32 v62, v62, v105
	s_waitcnt lgkmcnt(1)
	v_pk_fma_f32 v[54:55], v[46:47], v[50:51], v[54:55]
	v_pk_fma_f32 v[52:53], v[44:45], v[48:49], v[52:53]
	ds_read_b128 v[44:47], v87 offset:28672
	s_waitcnt lgkmcnt(1)
	v_mul_f32_e32 v48, v53, v57
	v_fmac_f32_e32 v48, v52, v56
	v_fmac_f32_e32 v48, v54, v58
	v_fmac_f32_e32 v48, v55, v59
	s_waitcnt lgkmcnt(0)
	v_mul_f32_e32 v45, v53, v45
	v_fmac_f32_e32 v45, v52, v44
	v_fmac_f32_e32 v45, v54, v46
	v_fmac_f32_e32 v45, v55, v47
	v_add_f32_e32 v56, v63, v48
	ds_read_b128 v[48:51], v87 offset:36864
	v_add_f32_e32 v57, v75, v45
	ds_read_b128 v[44:47], v87 offset:45056
	s_waitcnt lgkmcnt(1)
	v_mul_f32_e32 v49, v53, v49
	v_fmac_f32_e32 v49, v52, v48
	s_waitcnt lgkmcnt(0)
	v_mul_f32_e32 v45, v53, v45
	v_fmac_f32_e32 v45, v52, v44
	v_fmac_f32_e32 v49, v54, v50
	v_fmac_f32_e32 v45, v54, v46
	v_fmac_f32_e32 v49, v55, v51
	v_fmac_f32_e32 v45, v55, v47
	v_add_f32_e32 v58, v81, v49
	ds_read_b128 v[48:51], v87 offset:53248
	v_add_f32_e32 v59, v101, v45
	ds_read_b128 v[44:47], v87 offset:61440
	s_waitcnt lgkmcnt(1)
	v_mul_f32_e32 v49, v53, v49
	v_fmac_f32_e32 v49, v52, v48
	s_waitcnt lgkmcnt(0)
	v_mul_f32_e32 v45, v53, v45
	v_fmac_f32_e32 v45, v52, v44
	v_fmac_f32_e32 v49, v54, v50
	v_fmac_f32_e32 v45, v54, v46
	v_fmac_f32_e32 v49, v55, v51
	v_fmac_f32_e32 v45, v55, v47
	v_add_f32_e32 v63, v102, v49
	ds_read_b128 v[48:51], v92 offset:49152
	v_add_f32_e32 v75, v103, v45
	ds_read_b128 v[44:47], v92 offset:57344
	s_waitcnt lgkmcnt(1)
	v_mul_f32_e32 v49, v53, v49
	v_fmac_f32_e32 v49, v52, v48
	s_waitcnt lgkmcnt(0)
	v_mul_f32_e32 v101, v53, v45
	v_fmac_f32_e32 v101, v52, v44
	v_cvt_pk_bf16_f32 v44, v52, v53
	v_cvt_pk_bf16_f32 v45, v54, v55
	v_fmac_f32_e32 v49, v54, v50
	global_store_dwordx2 v[60:61], v[44:45], off offset:2048
	v_fmac_f32_e32 v49, v55, v51
	v_fmac_f32_e32 v101, v54, v46
	v_add_f32_e32 v81, v104, v49
	v_fmac_f32_e32 v101, v55, v47
	ds_read_b128 v[44:47], v87 offset:5120
	ds_read_b128 v[48:51], v87 offset:13312
	ds_read_b128 v[52:55], v87 offset:21504
	v_add_f32_e32 v62, v62, v101
	s_waitcnt lgkmcnt(1)
	v_pk_fma_f32 v[50:51], v[42:43], v[46:47], v[50:51]
	v_pk_fma_f32 v[48:49], v[40:41], v[44:45], v[48:49]
	ds_read_b128 v[40:43], v87 offset:29696
	s_waitcnt lgkmcnt(1)
	v_mul_f32_e32 v44, v49, v53
	v_fmac_f32_e32 v44, v48, v52
	v_fmac_f32_e32 v44, v50, v54
	v_fmac_f32_e32 v44, v51, v55
	s_waitcnt lgkmcnt(0)
	v_mul_f32_e32 v41, v49, v41
	v_fmac_f32_e32 v41, v48, v40
	v_fmac_f32_e32 v41, v50, v42
	v_fmac_f32_e32 v41, v51, v43
	v_add_f32_e32 v52, v56, v44
	ds_read_b128 v[44:47], v87 offset:37888
	v_add_f32_e32 v53, v57, v41
	ds_read_b128 v[40:43], v87 offset:46080
	s_waitcnt lgkmcnt(1)
	v_mul_f32_e32 v45, v49, v45
	v_fmac_f32_e32 v45, v48, v44
	s_waitcnt lgkmcnt(0)
	v_mul_f32_e32 v41, v49, v41
	v_fmac_f32_e32 v41, v48, v40
	v_fmac_f32_e32 v45, v50, v46
	v_fmac_f32_e32 v41, v50, v42
	v_fmac_f32_e32 v45, v51, v47
	v_fmac_f32_e32 v41, v51, v43
	v_add_f32_e32 v54, v58, v45
	ds_read_b128 v[44:47], v87 offset:54272
	v_add_f32_e32 v55, v59, v41
	ds_read_b128 v[40:43], v87 offset:62464
	s_waitcnt lgkmcnt(1)
	v_mul_f32_e32 v45, v49, v45
	v_fmac_f32_e32 v45, v48, v44
	s_waitcnt lgkmcnt(0)
	v_mul_f32_e32 v41, v49, v41
	v_fmac_f32_e32 v41, v48, v40
	v_fmac_f32_e32 v45, v50, v46
	v_fmac_f32_e32 v41, v50, v42
	v_fmac_f32_e32 v45, v51, v47
	v_fmac_f32_e32 v41, v51, v43
	v_add_f32_e32 v56, v63, v45
	ds_read_b128 v[44:47], v93 offset:49152
	v_add_f32_e32 v57, v75, v41
	ds_read_b128 v[40:43], v93 offset:57344
	s_waitcnt lgkmcnt(1)
	v_mul_f32_e32 v45, v49, v45
	v_fmac_f32_e32 v45, v48, v44
	s_waitcnt lgkmcnt(0)
	v_mul_f32_e32 v59, v49, v41
	v_fmac_f32_e32 v59, v48, v40
	v_cvt_pk_bf16_f32 v40, v48, v49
	v_cvt_pk_bf16_f32 v41, v50, v51
	v_fmac_f32_e32 v45, v50, v46
	global_store_dwordx2 v[60:61], v[40:41], off offset:2560
	v_fmac_f32_e32 v45, v51, v47
	v_fmac_f32_e32 v59, v50, v42
	v_add_f32_e32 v58, v81, v45
	v_fmac_f32_e32 v59, v51, v43
	ds_read_b128 v[40:43], v87 offset:6144
	ds_read_b128 v[44:47], v87 offset:14336
	ds_read_b128 v[48:51], v87 offset:22528
	v_add_f32_e32 v59, v62, v59
	s_waitcnt lgkmcnt(1)
	v_pk_fma_f32 v[46:47], v[38:39], v[42:43], v[46:47]
	v_pk_fma_f32 v[44:45], v[36:37], v[40:41], v[44:45]
	ds_read_b128 v[36:39], v87 offset:30720
	s_waitcnt lgkmcnt(1)
	v_mul_f32_e32 v40, v45, v49
	v_fmac_f32_e32 v40, v44, v48
	v_fmac_f32_e32 v40, v46, v50
	v_fmac_f32_e32 v40, v47, v51
	s_waitcnt lgkmcnt(0)
	v_mul_f32_e32 v37, v45, v37
	v_fmac_f32_e32 v37, v44, v36
	v_fmac_f32_e32 v37, v46, v38
	v_fmac_f32_e32 v37, v47, v39
	v_add_f32_e32 v48, v52, v40
	ds_read_b128 v[40:43], v87 offset:38912
	v_add_f32_e32 v49, v53, v37
	ds_read_b128 v[36:39], v87 offset:47104
	s_waitcnt lgkmcnt(1)
	v_mul_f32_e32 v41, v45, v41
	v_fmac_f32_e32 v41, v44, v40
	s_waitcnt lgkmcnt(0)
	v_mul_f32_e32 v37, v45, v37
	v_fmac_f32_e32 v37, v44, v36
	v_fmac_f32_e32 v41, v46, v42
	v_fmac_f32_e32 v37, v46, v38
	v_fmac_f32_e32 v41, v47, v43
	v_fmac_f32_e32 v37, v47, v39
	v_add_f32_e32 v50, v54, v41
	ds_read_b128 v[40:43], v87 offset:55296
	v_add_f32_e32 v51, v55, v37
	ds_read_b128 v[36:39], v87 offset:63488
	s_waitcnt lgkmcnt(1)
	v_mul_f32_e32 v41, v45, v41
	v_fmac_f32_e32 v41, v44, v40
	s_waitcnt lgkmcnt(0)
	v_mul_f32_e32 v37, v45, v37
	v_fmac_f32_e32 v37, v44, v36
	v_fmac_f32_e32 v41, v46, v42
	v_fmac_f32_e32 v37, v46, v38
	v_fmac_f32_e32 v41, v47, v43
	v_fmac_f32_e32 v37, v47, v39
	v_add_f32_e32 v52, v56, v41
	ds_read_b128 v[40:43], v94 offset:49152
	v_add_f32_e32 v53, v57, v37
	ds_read_b128 v[36:39], v94 offset:57344
	s_waitcnt lgkmcnt(1)
	v_mul_f32_e32 v41, v45, v41
	v_fmac_f32_e32 v41, v44, v40
	s_waitcnt lgkmcnt(0)
	v_mul_f32_e32 v55, v45, v37
	v_fmac_f32_e32 v55, v44, v36
	v_cvt_pk_bf16_f32 v36, v44, v45
	v_cvt_pk_bf16_f32 v37, v46, v47
	v_fmac_f32_e32 v41, v46, v42
	global_store_dwordx2 v[60:61], v[36:37], off offset:3072
	v_fmac_f32_e32 v41, v47, v43
	v_fmac_f32_e32 v55, v46, v38
	v_add_f32_e32 v54, v58, v41
	v_fmac_f32_e32 v55, v47, v39
	ds_read_b128 v[36:39], v87 offset:7168
	ds_read_b128 v[40:43], v87 offset:15360
	ds_read_b128 v[44:47], v87 offset:23552
	v_add_f32_e32 v55, v59, v55
	s_waitcnt lgkmcnt(1)
	v_pk_fma_f32 v[42:43], v[34:35], v[38:39], v[42:43]
	v_pk_fma_f32 v[40:41], v[32:33], v[36:37], v[40:41]
	ds_read_b128 v[32:35], v87 offset:31744
	s_waitcnt lgkmcnt(1)
	v_mul_f32_e32 v36, v41, v45
	v_fmac_f32_e32 v36, v40, v44
	v_fmac_f32_e32 v36, v42, v46
	v_fmac_f32_e32 v36, v43, v47
	s_waitcnt lgkmcnt(0)
	v_mul_f32_e32 v33, v41, v33
	v_fmac_f32_e32 v33, v40, v32
	v_fmac_f32_e32 v33, v42, v34
	v_fmac_f32_e32 v33, v43, v35
	v_add_f32_e32 v44, v48, v36
	ds_read_b128 v[36:39], v87 offset:39936
	v_add_f32_e32 v45, v49, v33
	ds_read_b128 v[32:35], v87 offset:48128
	s_waitcnt lgkmcnt(1)
	v_mul_f32_e32 v37, v41, v37
	v_fmac_f32_e32 v37, v40, v36
	s_waitcnt lgkmcnt(0)
	v_mul_f32_e32 v33, v41, v33
	v_fmac_f32_e32 v33, v40, v32
	v_fmac_f32_e32 v37, v42, v38
	v_fmac_f32_e32 v33, v42, v34
	v_fmac_f32_e32 v37, v43, v39
	v_fmac_f32_e32 v33, v43, v35
	v_add_f32_e32 v46, v50, v37
	ds_read_b128 v[36:39], v87 offset:56320
	v_add_f32_e32 v47, v51, v33
	ds_read_b128 v[32:35], v87 offset:64512
	s_waitcnt lgkmcnt(1)
	v_mul_f32_e32 v37, v41, v37
	v_fmac_f32_e32 v37, v40, v36
	s_waitcnt lgkmcnt(0)
	v_mul_f32_e32 v33, v41, v33
	v_fmac_f32_e32 v33, v40, v32
	v_fmac_f32_e32 v37, v42, v38
	v_fmac_f32_e32 v33, v42, v34
	v_fmac_f32_e32 v37, v43, v39
	v_fmac_f32_e32 v33, v43, v35
	v_add_f32_e32 v48, v52, v37
	ds_read_b128 v[36:39], v95 offset:49152
	v_add_f32_e32 v49, v53, v33
	ds_read_b128 v[32:35], v95 offset:57344
	s_waitcnt lgkmcnt(1)
	v_mul_f32_e32 v37, v41, v37
	v_fmac_f32_e32 v37, v40, v36
	s_waitcnt lgkmcnt(0)
	v_mul_f32_e32 v33, v41, v33
	v_fmac_f32_e32 v33, v40, v32
	v_fmac_f32_e32 v33, v42, v34
	v_fmac_f32_e32 v33, v43, v35
	v_add_f32_e32 v34, v55, v33
	v_cvt_pk_bf16_f32 v32, v40, v41
	v_cvt_pk_bf16_f32 v33, v42, v43
	global_store_dwordx2 v[60:61], v[32:33], off offset:3584
	v_add_f32_dpp v32, v44, v44 quad_perm:[1,0,3,2] row_mask:0xf bank_mask:0xf bound_ctrl:1
	v_fmac_f32_e32 v37, v42, v38
	v_fmac_f32_e32 v37, v43, v39
	v_add_f32_dpp v32, v32, v32 quad_perm:[2,3,0,1] row_mask:0xf bank_mask:0xf bound_ctrl:1
	v_add_f32_e32 v36, v54, v37
	s_nop 0
	v_add_f32_dpp v32, v32, v32 row_half_mirror row_mask:0xf bank_mask:0xf bound_ctrl:1
	s_nop 1
	v_add_f32_dpp v32, v32, v32 row_mirror row_mask:0xf bank_mask:0xf bound_ctrl:1
	s_nop 0
	v_readlane_b32 s40, v32, 0
	v_readlane_b32 s50, v32, 16
	v_readlane_b32 s36, v32, 32
	v_readlane_b32 s3, v32, 48
	v_add_f32_dpp v32, v45, v45 quad_perm:[1,0,3,2] row_mask:0xf bank_mask:0xf bound_ctrl:1
	s_nop 1
	v_add_f32_dpp v32, v32, v32 quad_perm:[2,3,0,1] row_mask:0xf bank_mask:0xf bound_ctrl:1
	s_nop 1
	v_add_f32_dpp v32, v32, v32 row_half_mirror row_mask:0xf bank_mask:0xf bound_ctrl:1
	s_nop 1
	v_add_f32_dpp v32, v32, v32 row_mirror row_mask:0xf bank_mask:0xf bound_ctrl:1
	s_nop 0
	v_readlane_b32 s49, v32, 0
	v_readlane_b32 s62, v32, 16
	v_readlane_b32 s41, v32, 32
	v_readlane_b32 s37, v32, 48
	v_add_f32_dpp v32, v46, v46 quad_perm:[1,0,3,2] row_mask:0xf bank_mask:0xf bound_ctrl:1
	s_nop 1
	v_add_f32_dpp v32, v32, v32 quad_perm:[2,3,0,1] row_mask:0xf bank_mask:0xf bound_ctrl:1
	s_nop 1
	v_add_f32_dpp v32, v32, v32 row_half_mirror row_mask:0xf bank_mask:0xf bound_ctrl:1
	s_nop 1
	v_add_f32_dpp v32, v32, v32 row_mirror row_mask:0xf bank_mask:0xf bound_ctrl:1
	s_nop 0
	v_readlane_b32 s53, v32, 0
	v_readlane_b32 s72, v32, 16
	v_readlane_b32 s51, v32, 32
	v_readlane_b32 s48, v32, 48
	v_add_f32_dpp v32, v47, v47 quad_perm:[1,0,3,2] row_mask:0xf bank_mask:0xf bound_ctrl:1
	s_nop 1
	v_add_f32_dpp v32, v32, v32 quad_perm:[2,3,0,1] row_mask:0xf bank_mask:0xf bound_ctrl:1
	s_nop 1
	v_add_f32_dpp v32, v32, v32 row_half_mirror row_mask:0xf bank_mask:0xf bound_ctrl:1
	s_nop 1
	v_add_f32_dpp v32, v32, v32 row_mirror row_mask:0xf bank_mask:0xf bound_ctrl:1
	s_nop 0
	v_readlane_b32 s67, v32, 0
	v_readlane_b32 s78, v32, 16
	v_readlane_b32 s63, v32, 32
	v_readlane_b32 s52, v32, 48
	v_add_f32_dpp v32, v48, v48 quad_perm:[1,0,3,2] row_mask:0xf bank_mask:0xf bound_ctrl:1
	s_nop 1
	v_add_f32_dpp v32, v32, v32 quad_perm:[2,3,0,1] row_mask:0xf bank_mask:0xf bound_ctrl:1
	s_nop 1
	v_add_f32_dpp v32, v32, v32 row_half_mirror row_mask:0xf bank_mask:0xf bound_ctrl:1
	s_nop 1
	v_add_f32_dpp v32, v32, v32 row_mirror row_mask:0xf bank_mask:0xf bound_ctrl:1
	s_nop 0
	v_readlane_b32 s77, v32, 0
	v_readlane_b32 s82, v32, 16
	v_readlane_b32 s73, v32, 32
	v_readlane_b32 s66, v32, 48
	v_add_f32_dpp v32, v49, v49 quad_perm:[1,0,3,2] row_mask:0xf bank_mask:0xf bound_ctrl:1
	s_nop 1
	v_add_f32_dpp v32, v32, v32 quad_perm:[2,3,0,1] row_mask:0xf bank_mask:0xf bound_ctrl:1
	s_nop 1
	v_add_f32_dpp v32, v32, v32 row_half_mirror row_mask:0xf bank_mask:0xf bound_ctrl:1
	s_nop 1
	v_add_f32_dpp v32, v32, v32 row_mirror row_mask:0xf bank_mask:0xf bound_ctrl:1
	s_nop 0
	v_readlane_b32 s81, v32, 0
	v_readlane_b32 s86, v32, 16
	v_readlane_b32 s79, v32, 32
	v_readlane_b32 s76, v32, 48
	v_add_f32_dpp v32, v36, v36 quad_perm:[1,0,3,2] row_mask:0xf bank_mask:0xf bound_ctrl:1
	s_nop 1
	v_add_f32_dpp v32, v32, v32 quad_perm:[2,3,0,1] row_mask:0xf bank_mask:0xf bound_ctrl:1
	s_nop 1
	v_add_f32_dpp v32, v32, v32 row_half_mirror row_mask:0xf bank_mask:0xf bound_ctrl:1
	s_nop 1
	v_add_f32_dpp v32, v32, v32 row_mirror row_mask:0xf bank_mask:0xf bound_ctrl:1
	s_nop 0
	v_readlane_b32 s85, v32, 0
	v_readlane_b32 s89, v32, 16
	v_readlane_b32 s83, v32, 32
	v_readlane_b32 s80, v32, 48
	v_add_f32_dpp v32, v34, v34 quad_perm:[1,0,3,2] row_mask:0xf bank_mask:0xf bound_ctrl:1
	s_nop 1
	v_add_f32_dpp v32, v32, v32 quad_perm:[2,3,0,1] row_mask:0xf bank_mask:0xf bound_ctrl:1
	s_nop 1
	v_add_f32_dpp v32, v32, v32 row_half_mirror row_mask:0xf bank_mask:0xf bound_ctrl:1
	s_nop 1
	v_add_f32_dpp v32, v32, v32 row_mirror row_mask:0xf bank_mask:0xf bound_ctrl:1
	s_nop 0
	v_readlane_b32 s88, v32, 0
	v_readlane_b32 s90, v32, 16
	v_readlane_b32 s87, v32, 32
	v_readlane_b32 s84, v32, 48
	s_and_saveexec_b64 s[34:35], s[6:7]
	s_cbranch_execz .LBB0_118
	v_mov_b32_e32 v41, s62
	v_mov_b32_e32 v42, s50
	v_mov_b32_e32 v40, s72
	v_add_f32_e32 v41, s49, v41
	v_add_f32_e32 v42, s40, v42
	v_mov_b32_e32 v39, s78
	v_add_f32_e32 v40, s53, v40
	v_add_f32_e32 v41, s41, v41
	v_add_f32_e32 v42, s36, v42
	v_mov_b32_e32 v38, s82
	v_add_f32_e32 v39, s67, v39
	v_add_f32_e32 v40, s51, v40
	v_add_f32_e32 v41, s37, v41
	v_add_f32_e32 v42, s3, v42
	v_mov_b32_e32 v37, s86
	v_add_f32_e32 v38, s77, v38
	v_add_f32_e32 v39, s63, v39
	v_add_f32_e32 v40, s48, v40
	v_cndmask_b32_e64 v41, v42, v41, s[8:9]
	v_mov_b32_e32 v36, s89
	v_add_f32_e32 v37, s81, v37
	v_add_f32_e32 v38, s73, v38
	v_add_f32_e32 v39, s52, v39
	v_cndmask_b32_e64 v40, v41, v40, s[10:11]
	v_mov_b32_e32 v35, s90
	v_add_f32_e32 v36, s85, v36
	v_add_f32_e32 v37, s79, v37
	v_add_f32_e32 v38, s66, v38
	v_cndmask_b32_e64 v39, v40, v39, s[12:13]
	v_add_f32_e32 v35, s88, v35
	v_add_f32_e32 v36, s83, v36
	v_add_f32_e32 v37, s76, v37
	v_cndmask_b32_e64 v38, v39, v38, s[14:15]
	v_add_f32_e32 v35, s87, v35
	v_add_f32_e32 v36, s80, v36
	v_cndmask_b32_e64 v37, v38, v37, s[16:17]
	v_add_f32_e32 v35, s84, v35
	v_cndmask_b32_e64 v36, v37, v36, s[18:19]
	v_lshlrev_b64 v[32:33], 5, v[82:83]
	v_cndmask_b32_e64 v35, v36, v35, s[20:21]
	v_lshl_add_u64 v[32:33], v[68:69], 0, v[32:33]
	v_add_f32_e32 v34, v35, v170
	global_store_dword v[32:33], v34, off
	s_branch .LBB0_118
